# lru_final / lru_agg: consumers the scheduler had placed inside the load bursts (forcing a full-latency stall mid-burst) moved after the last load; ml_conv loop no longer waits for its own stores
# speedup vs baseline: 1.0153x; 1.0153x over previous
.LBB0_596:
	s_or_b64 exec, exec, s[4:5]
	s_cmp_lt_i32 s12, 1
	s_cbranch_scc1 .LBB0_605
	v_lshlrev_b64 v[174:175], 13, v[190:191]
	v_mov_b32_e32 v171, v0
	v_lshl_add_u64 v[174:175], s[8:9], 0, v[174:175]
	v_lshl_add_u64 v[174:175], v[174:175], 0, v[170:171]
	global_load_dwordx4 v[174:177], v[174:175], off
	v_and_b32_e32 v1, 32, v172
	v_cmp_eq_u32_e32 vcc, 0, v1
	v_and_b32_e32 v1, 16, v172
	v_cmp_eq_u32_e64 s[4:5], 0, v1
	v_and_b32_e32 v1, 8, v172
	v_lshl_add_u64 v[224:225], s[8:9], 0, v[170:171]
	v_cmp_lt_i32_e64 s[8:9], v241, v235
	v_cmp_eq_u32_e64 s[6:7], 0, v1
	s_waitcnt vmcnt(39)
	v_mov_b32_e32 v170, v15
	v_cndmask_b32_e64 v1, v234, v241, s[8:9]
	v_cmp_lt_i32_e64 s[8:9], v240, v235
	v_mov_b32_e32 v173, v7
	s_waitcnt vmcnt(34)
	v_mov_b32_e32 v7, v35
	v_cndmask_b32_e64 v15, v234, v240, s[8:9]
	v_lshlrev_b32_e32 v247, 2, v15
	v_xor_b32_e32 v15, 8, v234
	v_cmp_lt_i32_e64 s[8:9], v15, v235
	v_mov_b32_e32 v171, v17
	v_mov_b32_e32 v186, v9
	v_cndmask_b32_e64 v15, v234, v15, s[8:9]
	v_lshlrev_b32_e32 v248, 2, v15
	v_xor_b32_e32 v15, 4, v234
	v_cmp_lt_i32_e64 s[8:9], v15, v235
	v_mov_b32_e32 v9, v37
	v_mov_b32_e32 v35, v26
	v_cndmask_b32_e64 v15, v234, v15, s[8:9]
	v_lshlrev_b32_e32 v249, 2, v15
	v_xor_b32_e32 v15, 2, v234
	v_cmp_lt_i32_e64 s[8:9], v15, v235
	v_mov_b32_e32 v26, v7
	v_mov_b32_e32 v7, v22
	v_cndmask_b32_e64 v15, v234, v15, s[8:9]
	v_lshlrev_b32_e32 v250, 2, v15
	v_xor_b32_e32 v15, 1, v234
	v_cmp_lt_i32_e64 s[8:9], v15, v235
	v_mov_b32_e32 v22, v173
	v_lshrrev_b32_e32 v173, 1, v172
	v_cndmask_b32_e64 v15, v234, v15, s[8:9]
	v_lshlrev_b32_e32 v251, 2, v15
	v_and_b32_e32 v15, 7, v172
	v_cmp_eq_u32_e64 s[8:9], 0, v15
	v_mov_b32_e32 v15, v18
	v_mov_b32_e32 v18, v170
	v_mov_b32_e32 v17, v20
	v_mov_b32_e32 v37, v28
	v_mov_b32_e32 v20, v171
	v_mov_b32_e32 v28, v9
	v_mov_b32_e32 v9, v24
	v_mov_b32_e32 v24, v186
	v_lshlrev_b64 v[170:171], 7, v[190:191]
	v_and_b32_e32 v186, 0x60, v173
	v_and_b32_e32 v173, 28, v173
	v_or3_b32 v170, v170, v186, v173
	v_lshl_add_u64 v[170:171], s[2:3], 0, v[170:171]
	s_mov_b64 s[10:11], 0x1c200000
	v_lshl_add_u64 v[226:227], v[170:171], 0, s[10:11]
	v_lshlrev_b64 v[170:171], 12, v[190:191]
	v_and_b32_e32 v172, 0xff, v172
	v_lshl_or_b32 v170, v172, 4, v170
	s_waitcnt vmcnt(33)
	v_mov_b32_e32 v187, v39
	v_mov_b32_e32 v188, v41
	v_lshl_add_u64 v[170:171], s[2:3], 0, v[170:171]
	s_mov_b64 s[2:3], 0x13200000
	s_mov_b32 s13, 0
	v_lshlrev_b32_e32 v1, 2, v1
	v_mov_b32_e32 v39, v30
	v_mov_b32_e32 v30, v187
	v_mov_b32_e32 v41, v32
	v_mov_b32_e32 v32, v188
	v_lshl_add_u64 v[228:229], v[170:171], 0, s[2:3]
	s_waitcnt vmcnt(0)
	s_branch .LBB0_599
.LBB0_598:
	s_or_b64 exec, exec, s[2:3]
	s_mov_b64 s[2:3], 0x1000
	s_waitcnt vmcnt(2) lgkmcnt(0)
	v_mov_b64_e32 v[176:177], v[172:173]
	v_lshl_add_u64 v[226:227], v[226:227], 0, s[0:1]
	v_lshl_add_u64 v[228:229], v[228:229], 0, s[2:3]
	s_cmp_lg_u32 s12, s13
	v_mov_b32_e32 v192, v193
	v_mov_b32_e32 v194, v195
	v_mov_b32_e32 v196, v197
	v_mov_b32_e32 v198, v199
	v_mov_b32_e32 v200, v201
	v_mov_b32_e32 v202, v203
	v_mov_b32_e32 v204, v205
	v_mov_b32_e32 v206, v207
	v_mov_b64_e32 v[174:175], v[170:171]
	v_mov_b32_e32 v193, v209
	v_mov_b32_e32 v195, v211
	v_mov_b32_e32 v197, v213
	v_mov_b32_e32 v199, v215
	v_mov_b32_e32 v201, v217
	v_mov_b32_e32 v203, v219
	v_mov_b32_e32 v205, v221
	v_mov_b32_e32 v207, v223
	s_cbranch_scc0 .LBB0_605

.LBB0_601:
	s_or_b64 exec, exec, s[2:3]
	s_add_i32 s13, s13, 1
	s_nop 0
	v_mov_b64_e32 v[170:171], v[174:175]
	s_cmp_ge_i32 s13, s12
	v_mov_b64_e32 v[172:173], v[176:177]
	s_cbranch_scc1 .LBB0_603
	v_add_u32_e32 v170, 1, v191
	v_ashrrev_i32_e32 v171, 31, v170
	v_lshlrev_b64 v[170:171], 13, v[170:171]
	v_lshl_add_u64 v[170:171], v[224:225], 0, v[170:171]
	global_load_dwordx4 v[170:173], v[170:171], off

.LBB0_1272:
	v_lshl_add_u64 v[20:21], s[4:5], 0, v[18:19]
	s_waitcnt vmcnt(3)
	v_add_co_u32_e32 v22, vcc, 0x3201000, v20
	v_lshl_add_u64 v[24:25], s[4:5], 0, v[16:17]
	s_nop 0
	v_addc_co_u32_e32 v23, vcc, 0, v21, vcc
	global_load_dword v1, v[22:23], off offset:2048
	global_load_dword v27, v[22:23], off
	v_add_co_u32_e32 v22, vcc, 0x3200000, v20
	s_add_i32 s3, s3, 8
	s_nop 0
	v_addc_co_u32_e32 v23, vcc, 0, v21, vcc
	v_add_co_u32_e32 v24, vcc, 0x3100000, v24
	global_load_dword v31, v[22:23], off offset:2048
	s_nop 0
	v_addc_co_u32_e32 v25, vcc, 0, v25, vcc
	s_waitcnt vmcnt(5)
	v_add_co_u32_e32 v28, vcc, 0x3203000, v20
	global_load_dword v26, v[24:25], off
	s_nop 0
	v_addc_co_u32_e32 v29, vcc, 0, v21, vcc
	global_load_dword v35, v[28:29], off offset:3072
	global_load_dword v39, v[28:29], off offset:1024
	v_add_co_u32_e32 v28, vcc, 0x3202000, v20
	v_lshl_add_u64 v[16:17], v[16:17], 0, 64
	s_nop 0
	v_addc_co_u32_e32 v29, vcc, 0, v21, vcc
	s_waitcnt vmcnt(7)
	v_add_co_u32_e32 v32, vcc, 0x3206000, v20
	global_load_dword v43, v[28:29], off offset:3072
	global_load_dword v30, v[24:25], off offset:8
	v_addc_co_u32_e32 v33, vcc, 0, v21, vcc
	global_load_dword v47, v[32:33], off
	v_add_co_u32_e32 v32, vcc, 0x3205000, v20
	v_lshl_add_u64 v[18:19], v[18:19], 0, s[6:7]
	s_nop 0
	v_addc_co_u32_e32 v33, vcc, 0, v21, vcc
	v_add_co_u32_e32 v36, vcc, 0x3208000, v20
	global_load_dword v51, v[32:33], off offset:2048
	global_load_dword v54, v[32:33], off
	global_load_dword v34, v[24:25], off offset:16
	v_addc_co_u32_e32 v37, vcc, 0, v21, vcc
	global_load_dword v55, v[36:37], off offset:1024
	v_add_co_u32_e32 v36, vcc, 0x3207000, v20
	s_cmp_lt_u32 s3, 56
	s_nop 0
	v_addc_co_u32_e32 v37, vcc, 0, v21, vcc
	v_add_co_u32_e32 v40, vcc, 0x320a000, v20
	global_load_dword v56, v[36:37], off offset:3072
	global_load_dword v57, v[36:37], off offset:1024
	global_load_dword v38, v[24:25], off offset:24
	v_addc_co_u32_e32 v41, vcc, 0, v21, vcc
	global_load_dword v58, v[40:41], off offset:2048
	global_load_dword v59, v[40:41], off
	v_add_co_u32_e32 v40, vcc, 0x3209000, v20
	s_nop 0
	s_nop 0
	v_addc_co_u32_e32 v41, vcc, 0, v21, vcc
	v_add_co_u32_e32 v44, vcc, 0x320c000, v20
	global_load_dword v60, v[40:41], off offset:2048
	global_load_dword v42, v[24:25], off offset:32
	v_addc_co_u32_e32 v45, vcc, 0, v21, vcc
	global_load_dword v61, v[44:45], off offset:3072
	global_load_dword v62, v[44:45], off offset:1024
	v_add_co_u32_e32 v44, vcc, 0x320b000, v20
	s_nop 0
	s_nop 0
	v_addc_co_u32_e32 v45, vcc, 0, v21, vcc
	v_add_co_u32_e32 v48, vcc, 0x320f000, v20
	global_load_dword v63, v[44:45], off offset:3072
	global_load_dword v46, v[24:25], off offset:40
	v_addc_co_u32_e32 v49, vcc, 0, v21, vcc
	global_load_dword v64, v[48:49], off
	v_add_co_u32_e32 v48, vcc, 0x320e000, v20
	s_nop 1
	v_addc_co_u32_e32 v49, vcc, 0, v21, vcc
	global_load_dword v65, v[48:49], off offset:2048
	global_load_dword v66, v[48:49], off
	global_load_dword v50, v[24:25], off offset:48
	v_add_co_u32_e32 v52, vcc, 0x3211000, v20
	s_nop 1
	v_addc_co_u32_e32 v53, vcc, 0, v21, vcc
	global_load_dword v67, v[52:53], off offset:1024
	v_add_co_u32_e32 v20, vcc, 0x3210000, v20
	s_nop 0
	s_nop 0
	v_addc_co_u32_e32 v21, vcc, 0, v21, vcc
	global_load_dword v68, v[20:21], off offset:3072
	global_load_dword v69, v[20:21], off offset:1024
	s_nop 0
	global_load_dword v24, v[24:25], off offset:56
	s_waitcnt vmcnt(29)
	v_lshlrev_b32_e32 v70, 16, v27
	v_and_b32_e32 v71, 0xffff0000, v27
	v_and_b32_e32 v53, 0xffff0000, v31
	v_lshlrev_b32_e32 v25, 16, v1
	v_mul_f32_e32 v52, 0x3fb8aa3b, v25
	v_exp_f32_e32 v52, v52
	v_and_b32_e32 v1, 0xffff0000, v1
	v_add_f32_e32 v4, v4, v1
	v_add_f32_e32 v2, v2, v25
	v_fmac_f32_e32 v70, v3, v52
	v_lshlrev_b32_e32 v52, 16, v31
	s_waitcnt vmcnt(28)
	v_pk_mul_f32 v[26:27], v[26:27], v[52:53] op_sel_hi:[0,1]
	v_mul_f32_e32 v3, 0x3fb8aa3b, v1
	v_pk_mul_f32 v[26:27], v[14:15], v[26:27]
	v_exp_f32_e32 v3, v3
	v_cvt_pk_bf16_f32 v1, v26, v27
	global_store_dword v[22:23], v1, off offset:2048
	s_waitcnt vmcnt(26)
	v_lshlrev_b32_e32 v22, 16, v43
	v_and_b32_e32 v23, 0xffff0000, v43
	s_waitcnt vmcnt(25)
	v_pk_mul_f32 v[22:23], v[30:31], v[22:23] op_sel_hi:[0,1]
	v_pk_mul_f32 v[22:23], v[14:15], v[22:23]
	v_fmac_f32_e32 v71, v5, v3
	v_cvt_pk_bf16_f32 v3, v22, v23
	global_store_dword v[28:29], v3, off offset:3072
	s_waitcnt vmcnt(23)
	v_lshlrev_b32_e32 v28, 16, v54
	v_and_b32_e32 v29, 0xffff0000, v54
	s_waitcnt vmcnt(22)
	v_pk_mul_f32 v[28:29], v[34:35], v[28:29] op_sel_hi:[0,1]
	v_pk_mul_f32 v[28:29], v[14:15], v[28:29]
	v_lshlrev_b32_e32 v23, 16, v51
	v_cvt_pk_bf16_f32 v28, v28, v29
	global_store_dword v[32:33], v28, off
	s_waitcnt vmcnt(20)
	v_lshlrev_b32_e32 v28, 16, v57
	v_and_b32_e32 v29, 0xffff0000, v57
	s_waitcnt vmcnt(19)
	v_pk_mul_f32 v[28:29], v[38:39], v[28:29] op_sel_hi:[0,1]
	v_pk_mul_f32 v[28:29], v[14:15], v[28:29]
	v_and_b32_e32 v27, 0xffff0000, v51
	v_cvt_pk_bf16_f32 v28, v28, v29
	global_store_dword v[36:37], v28, off offset:1024
	s_waitcnt vmcnt(19)
	v_lshlrev_b32_e32 v28, 16, v58
	v_mul_f32_e32 v29, 0x3fb8aa3b, v28
	v_lshlrev_b32_e32 v43, 16, v56
	v_exp_f32_e32 v51, v29
	v_and_b32_e32 v30, 0xffff0000, v58
	v_mul_f32_e32 v29, 0x3fb8aa3b, v30
	v_lshlrev_b32_e32 v22, 16, v47
	v_and_b32_e32 v26, 0xffff0000, v47
	v_and_b32_e32 v47, 0xffff0000, v56
	v_exp_f32_e32 v52, v29
	v_mul_f32_e32 v3, 0x3fb8aa3b, v22
	s_waitcnt vmcnt(17)
	v_lshlrev_b32_e32 v32, 16, v60
	v_and_b32_e32 v33, 0xffff0000, v60
	s_waitcnt vmcnt(16)
	v_pk_mul_f32 v[32:33], v[42:43], v[32:33] op_sel_hi:[0,1]
	v_pk_mul_f32 v[32:33], v[14:15], v[32:33]
	v_exp_f32_e32 v3, v3
	v_cvt_pk_bf16_f32 v29, v32, v33
	global_store_dword v[40:41], v29, off offset:2048
	v_lshlrev_b32_e32 v1, 16, v39
	v_lshlrev_b32_e32 v38, 16, v55
	v_and_b32_e32 v5, 0xffff0000, v39
	s_waitcnt vmcnt(15)
	v_lshlrev_b32_e32 v39, 16, v62
	s_waitcnt vmcnt(14)
	v_lshlrev_b32_e32 v32, 16, v63
	v_and_b32_e32 v33, 0xffff0000, v63
	s_waitcnt vmcnt(13)
	v_pk_mul_f32 v[32:33], v[46:47], v[32:33] op_sel_hi:[0,1]
	v_pk_mul_f32 v[32:33], v[14:15], v[32:33]
	v_mul_f32_e32 v25, 0x3fb8aa3b, v26
	v_cvt_pk_bf16_f32 v29, v32, v33
	s_waitcnt vmcnt(12)
	v_lshlrev_b32_e32 v32, 16, v64
	global_store_dword v[44:45], v29, off offset:3072
	v_mul_f32_e32 v29, 0x3fb8aa3b, v32
	s_waitcnt vmcnt(11)
	v_lshlrev_b32_e32 v36, 16, v66
	v_and_b32_e32 v37, 0xffff0000, v66
	s_waitcnt vmcnt(10)
	v_pk_mul_f32 v[36:37], v[50:51], v[36:37] op_sel_hi:[0,1]
	v_pk_mul_f32 v[36:37], v[14:15], v[36:37]
	v_exp_f32_e32 v29, v29
	v_cvt_pk_bf16_f32 v33, v36, v37
	v_lshlrev_b32_e32 v36, 16, v35
	global_store_dword v[48:49], v33, off
	v_mul_f32_e32 v33, 0x3fb8aa3b, v36
	v_exp_f32_e32 v33, v33
	v_lshlrev_b32_e32 v37, 16, v59
	v_exp_f32_e32 v25, v25
	v_and_b32_e32 v34, 0xffff0000, v64
	v_fmac_f32_e32 v1, v70, v33
	v_fmac_f32_e32 v23, v1, v3
	v_mul_f32_e32 v1, 0x3fb8aa3b, v38
	v_exp_f32_e32 v1, v1
	v_mul_f32_e32 v31, 0x3fb8aa3b, v34
	v_exp_f32_e32 v31, v31
	v_fmac_f32_e32 v43, v23, v1
	v_mul_f32_e32 v3, v43, v51
	v_pk_add_f32 v[2:3], v[2:3], v[36:37]
	v_lshlrev_b32_e32 v36, 16, v61
	v_mul_f32_e32 v1, 0x3fb8aa3b, v36
	v_exp_f32_e32 v23, v1
	v_lshlrev_b32_e32 v37, 16, v65
	v_pk_add_f32 v[40:41], v[2:3], v[22:23]
	v_pk_mul_f32 v[2:3], v[2:3], v[22:23]
	s_nop 0
	v_mov_b32_e32 v41, v3
	v_pk_add_f32 v[2:3], v[40:41], v[38:39]
	s_nop 0
	v_pk_add_f32 v[22:23], v[2:3], v[28:29]
	v_pk_mul_f32 v[2:3], v[2:3], v[28:29]
	s_nop 0
	v_mov_b32_e32 v23, v3
	v_pk_add_f32 v[2:3], v[22:23], v[36:37]
	s_waitcnt vmcnt(10)
	v_lshlrev_b32_e32 v22, 16, v67
	v_mul_f32_e32 v1, 0x3fb8aa3b, v22
	v_exp_f32_e32 v33, v1
	s_waitcnt vmcnt(9)
	v_lshlrev_b32_e32 v23, 16, v68
	v_pk_add_f32 v[28:29], v[2:3], v[32:33]
	v_pk_mul_f32 v[2:3], v[2:3], v[32:33]
	v_and_b32_e32 v32, 0xffff0000, v55
	v_and_b32_e32 v2, 0xffff0000, v35
	v_mul_f32_e32 v1, 0x3fb8aa3b, v2
	v_exp_f32_e32 v1, v1
	v_mov_b32_e32 v29, v3
	v_and_b32_e32 v3, 0xffff0000, v59
	v_and_b32_e32 v33, 0xffff0000, v62
	v_fmac_f32_e32 v5, v71, v1
	v_mul_f32_e32 v1, 0x3fb8aa3b, v32
	v_exp_f32_e32 v1, v1
	v_fmac_f32_e32 v27, v5, v25
	v_fmac_f32_e32 v47, v27, v1
	v_mul_f32_e32 v5, v47, v52
	v_pk_add_f32 v[2:3], v[4:5], v[2:3]
	v_and_b32_e32 v4, 0xffff0000, v61
	v_mul_f32_e32 v1, 0x3fb8aa3b, v4
	v_exp_f32_e32 v27, v1
	v_and_b32_e32 v5, 0xffff0000, v65
	v_pk_add_f32 v[36:37], v[2:3], v[26:27]
	v_pk_mul_f32 v[2:3], v[2:3], v[26:27]
	s_nop 0
	v_mov_b32_e32 v37, v3
	v_pk_add_f32 v[2:3], v[36:37], v[32:33]
	s_nop 0
	v_pk_add_f32 v[26:27], v[2:3], v[30:31]
	v_pk_mul_f32 v[2:3], v[2:3], v[30:31]
	s_nop 0
	v_mov_b32_e32 v27, v3
	v_pk_add_f32 v[2:3], v[26:27], v[4:5]
	v_and_b32_e32 v4, 0xffff0000, v67
	v_mul_f32_e32 v1, 0x3fb8aa3b, v4
	v_exp_f32_e32 v35, v1
	v_and_b32_e32 v5, 0xffff0000, v68
	v_pk_add_f32 v[26:27], v[2:3], v[34:35]
	v_pk_mul_f32 v[2:3], v[2:3], v[34:35]
	s_nop 0
	v_mov_b32_e32 v27, v3
	v_pk_add_f32 v[2:3], v[28:29], v[22:23]
	s_waitcnt vmcnt(8)
	v_lshlrev_b32_e32 v22, 16, v69
	v_and_b32_e32 v23, 0xffff0000, v69
	s_waitcnt vmcnt(7)
	v_pk_mul_f32 v[22:23], v[24:25], v[22:23] op_sel_hi:[0,1]
	v_pk_mul_f32 v[22:23], v[14:15], v[22:23]
	v_pk_add_f32 v[4:5], v[26:27], v[4:5]
	v_cvt_pk_bf16_f32 v1, v22, v23
	global_store_dword v[20:21], v1, off offset:1024
	s_cbranch_scc1 .LBB0_1272
	s_ashr_i32 s3, s2, 31
	s_lshl_b64 s[6:7], s[2:3], 13
	v_lshl_add_u64 v[14:15], v[8:9], 0, s[6:7]
	s_mov_b32 s3, s70
	global_store_dwordx4 v[14:15], v[2:5], off
	s_add_i32 s2, s3, s2
	s_cmpk_lt_i32 s2, 0x200
	s_cbranch_scc1 .LBB0_1271

.LBB0_1330:
	v_add_co_u32_e32 v2, vcc, 0xffff2000, v30
	s_movk_i32 s6, 0x8000
	s_nop 0
	v_addc_co_u32_e32 v3, vcc, -1, v31, vcc
	v_add_co_u32_e32 v4, vcc, 0xffff4000, v30
	global_load_dwordx4 v[14:17], v[2:3], off
	s_nop 0
	v_addc_co_u32_e32 v5, vcc, -1, v31, vcc
	global_load_dwordx4 v[18:21], v[4:5], off
	v_add_co_u32_e32 v2, vcc, 0xffff6000, v30
	s_nop 0
	s_nop 0
	v_addc_co_u32_e32 v3, vcc, -1, v31, vcc
	v_add_co_u32_e32 v4, vcc, s6, v30
	s_movk_i32 s6, 0xa000
	s_nop 0
	v_addc_co_u32_e32 v5, vcc, -1, v31, vcc
	v_add_co_u32_e32 v6, vcc, s6, v30
	global_load_dwordx4 v[10:13], v[2:3], off
	s_nop 0
	v_addc_co_u32_e32 v7, vcc, -1, v31, vcc
	s_movk_i32 s6, 0xc000
	v_add_co_u32_e32 v32, vcc, s6, v30
	global_load_dwordx4 v[6:9], v[6:7], off
	s_nop 0
	v_addc_co_u32_e32 v33, vcc, -1, v31, vcc
	global_load_dwordx4 v[2:5], v[4:5], off
	s_movk_i32 s6, 0xe000
	v_add_co_u32_e32 v36, vcc, s6, v30
	global_load_dwordx4 v[32:35], v[32:33], off
	s_nop 0
	v_addc_co_u32_e32 v37, vcc, -1, v31, vcc
	global_load_dwordx4 v[36:39], v[36:37], off
	s_nop 0
	global_load_dwordx4 v[40:43], v[30:31], off
	s_waitcnt vmcnt(7)
	v_mul_f32_e32 v1, 0x3fb8aa3b, v14
	v_mul_f32_e32 v16, 0x3fb8aa3b, v16
	v_mov_b32_e32 v14, v17
	v_exp_f32_e32 v17, v1
	v_exp_f32_e32 v16, v16
	s_waitcnt vmcnt(6)
	v_mul_f32_e32 v1, 0x3fb8aa3b, v18
	v_mul_f32_e32 v20, 0x3fb8aa3b, v20
	v_mov_b32_e32 v18, v21
	v_exp_f32_e32 v21, v1
	v_exp_f32_e32 v20, v20
	v_pk_fma_f32 v[14:15], v[28:29], v[16:17], v[14:15]
	s_mov_b32 s6, s3
	s_add_i32 s3, s3, 8
	v_pk_fma_f32 v[14:15], v[20:21], v[14:15], v[18:19]
	s_add_i32 s6, s6, 16
	s_cmp_gt_u32 s6, s5
	v_lshl_add_u64 v[30:31], v[30:31], 0, s[8:9]
	s_waitcnt vmcnt(5)
	v_mul_f32_e32 v1, 0x3fb8aa3b, v10
	v_mul_f32_e32 v12, 0x3fb8aa3b, v12
	v_mov_b32_e32 v10, v13
	v_exp_f32_e32 v13, v1
	v_exp_f32_e32 v12, v12
	s_waitcnt vmcnt(4)
	v_mul_f32_e32 v8, 0x3fb8aa3b, v8
	v_exp_f32_e32 v8, v8
	v_pk_fma_f32 v[10:11], v[12:13], v[14:15], v[10:11]
	s_waitcnt vmcnt(3)
	v_mul_f32_e32 v1, 0x3fb8aa3b, v2
	v_mul_f32_e32 v4, 0x3fb8aa3b, v4
	v_mov_b32_e32 v2, v5
	v_exp_f32_e32 v5, v1
	v_exp_f32_e32 v4, v4
	v_mul_f32_e32 v1, 0x3fb8aa3b, v6
	v_mov_b32_e32 v6, v9
	v_exp_f32_e32 v9, v1
	s_waitcnt vmcnt(2)
	v_mul_f32_e32 v1, 0x3fb8aa3b, v32
	v_mul_f32_e32 v16, 0x3fb8aa3b, v34
	v_exp_f32_e32 v17, v1
	v_exp_f32_e32 v16, v16
	s_waitcnt vmcnt(1)
	v_mul_f32_e32 v1, 0x3fb8aa3b, v36
	v_mul_f32_e32 v18, 0x3fb8aa3b, v38
	s_waitcnt vmcnt(0)
	v_mul_f32_e32 v19, 0x3fb8aa3b, v40
	v_mul_f32_e32 v20, 0x3fb8aa3b, v42
	v_exp_f32_e32 v13, v1
	v_exp_f32_e32 v12, v18
	v_exp_f32_e32 v15, v19
	v_exp_f32_e32 v14, v20
	v_pk_fma_f32 v[2:3], v[4:5], v[10:11], v[2:3]
	v_mov_b32_e32 v32, v35
	v_pk_fma_f32 v[2:3], v[8:9], v[2:3], v[6:7]
	v_mov_b32_e32 v36, v39
	v_pk_fma_f32 v[2:3], v[16:17], v[2:3], v[32:33]
	v_mov_b32_e32 v40, v43
	v_pk_fma_f32 v[2:3], v[12:13], v[2:3], v[36:37]
	s_nop 0
	v_pk_fma_f32 v[28:29], v[14:15], v[2:3], v[40:41]
	s_cbranch_scc0 .LBB0_1330
	s_cmp_ge_u32 s3, s5
	s_cbranch_scc0 .LBB0_1333
	s_branch .LBB0_1335

.LBB0_1336:
	v_add_co_u32_e32 v4, vcc, 0x1000, v2
	s_mov_b32 s3, 0xa000
	s_nop 0
	v_addc_co_u32_e32 v5, vcc, 0, v3, vcc
	global_load_dword v1, v[4:5], off offset:2048
	global_load_dword v21, v[4:5], off
	global_load_dword v31, v[2:3], off
	v_add_co_u32_e32 v4, vcc, 0x3000, v2
	s_add_i32 s2, s2, 8
	s_nop 0
	v_addc_co_u32_e32 v5, vcc, 0, v3, vcc
	global_load_dword v32, v[4:5], off offset:3072
	global_load_dword v33, v[4:5], off offset:1024
	v_add_co_u32_e32 v16, vcc, 0x2000, v2
	s_cmp_gt_u32 s2, 55
	s_nop 0
	v_addc_co_u32_e32 v17, vcc, 0, v3, vcc
	global_load_dword v34, v[16:17], off offset:1024
	v_add_co_u32_e32 v6, vcc, s31, v2
	s_nop 0
	s_nop 0
	v_addc_co_u32_e32 v7, vcc, 0, v3, vcc
	v_add_co_u32_e32 v4, vcc, 0x5000, v2
	global_load_dword v35, v[6:7], off
	s_nop 0
	v_addc_co_u32_e32 v5, vcc, 0, v3, vcc
	v_add_co_u32_e32 v14, vcc, s34, v2
	global_load_dword v36, v[4:5], off offset:2048
	s_nop 0
	v_addc_co_u32_e32 v15, vcc, 0, v3, vcc
	global_load_dword v37, v[14:15], off offset:2048
	v_add_co_u32_e32 v4, vcc, s5, v2
	s_nop 0
	s_nop 0
	v_addc_co_u32_e32 v5, vcc, 0, v3, vcc
	global_load_dword v38, v[4:5], off offset:1024
	v_add_co_u32_e32 v4, vcc, 0x7000, v2
	s_nop 0
	s_nop 0
	v_addc_co_u32_e32 v5, vcc, 0, v3, vcc
	global_load_dword v39, v[4:5], off offset:3072
	global_load_dword v40, v[6:7], off offset:3072
	v_add_co_u32_e32 v4, vcc, s3, v2
	s_mov_b32 s3, 0x9000
	s_nop 0
	v_addc_co_u32_e32 v5, vcc, 0, v3, vcc
	v_add_co_u32_e32 v12, vcc, s3, v2
	s_mov_b32 s3, 0xc000
	s_nop 0
	v_addc_co_u32_e32 v13, vcc, 0, v3, vcc
	global_load_dword v41, v[4:5], off offset:2048
	global_load_dword v42, v[4:5], off
	v_add_co_u32_e32 v4, vcc, s3, v2
	s_mov_b32 s3, 0xb000
	s_nop 0
	v_addc_co_u32_e32 v5, vcc, 0, v3, vcc
	v_add_co_u32_e32 v10, vcc, s3, v2
	s_mov_b32 s3, 0xf000
	s_nop 0
	v_addc_co_u32_e32 v11, vcc, 0, v3, vcc
	global_load_dword v43, v[12:13], off
	global_load_dword v44, v[4:5], off offset:3072
	global_load_dword v45, v[4:5], off offset:1024
	v_add_co_u32_e32 v4, vcc, s3, v2
	s_mov_b32 s3, 0xe000
	s_nop 0
	v_addc_co_u32_e32 v5, vcc, 0, v3, vcc
	v_add_co_u32_e32 v8, vcc, s3, v2
	s_mov_b32 s3, 0xd000
	s_nop 0
	v_addc_co_u32_e32 v9, vcc, 0, v3, vcc
	global_load_dword v46, v[10:11], off offset:1024
	global_load_dword v48, v[4:5], off
	global_load_dword v50, v[8:9], off offset:2048
	v_add_co_u32_e32 v8, vcc, s3, v2
	s_mov_b32 s3, 0x11000
	s_nop 0
	v_addc_co_u32_e32 v9, vcc, 0, v3, vcc
	v_add_co_u32_e32 v18, vcc, s3, v2
	global_load_dword v51, v[8:9], off offset:2048
	s_nop 0
	v_addc_co_u32_e32 v19, vcc, 0, v3, vcc
	global_load_dword v52, v[18:19], off offset:1024
	v_add_co_u32_e32 v18, vcc, s35, v2
	s_nop 0
	s_nop 0
	v_addc_co_u32_e32 v19, vcc, 0, v3, vcc
	global_load_dword v54, v[18:19], off offset:3072
	global_load_dword v56, v[4:5], off offset:3072
	s_waitcnt vmcnt(21)
	v_lshlrev_b32_e32 v20, 16, v21
	v_and_b32_e32 v21, 0xffff0000, v21
	v_lshlrev_b32_e32 v30, 16, v31
	v_and_b32_e32 v31, 0xffff0000, v31
	v_lshlrev_b32_e32 v18, 16, v1
	v_and_b32_e32 v1, 0xffff0000, v1
	v_mul_f32_e32 v18, 0x3fb8aa3b, v18
	v_mul_f32_e32 v1, 0x3fb8aa3b, v1
	v_exp_f32_e32 v19, v18
	v_exp_f32_e32 v18, v1
	v_mul_f32_e32 v1, 0x3d372713, v30
	v_mul_f32_e32 v1, v1, v30
	v_pk_mul_f32 v[18:19], v[28:29], v[18:19]
	s_nop 0
	v_pk_add_f32 v[18:19], v[18:19], v[20:21] op_sel:[1,0] op_sel_hi:[0,1]
	v_mov_b32_e32 v20, v30
	v_fmac_f32_e32 v20, v1, v20
	v_mul_f32_e32 v1, 0x3f4c422a, v20
	v_add_f32_e32 v1, v1, v1
	v_mul_f32_e32 v1, 0x3fb8aa3b, v1
	v_exp_f32_e32 v1, v1
	v_mov_b32_e32 v21, v31
	v_pk_mul_f32 v[28:29], v[30:31], 0.5 op_sel_hi:[1,0]
	s_waitcnt vmcnt(18)
	v_lshlrev_b32_e32 v30, 16, v34
	v_add_f32_e32 v1, 1.0, v1
	v_rcp_f32_e32 v20, v1
	v_mul_f32_e32 v1, 0x3d372713, v31
	v_mul_f32_e32 v1, v1, v31
	v_fmac_f32_e32 v21, v1, v21
	v_mul_f32_e32 v1, 0x3f4c422a, v21
	v_add_f32_e32 v1, v1, v1
	v_mul_f32_e32 v1, 0x3fb8aa3b, v1
	v_exp_f32_e32 v1, v1
	v_and_b32_e32 v31, 0xffff0000, v34
	v_add_f32_e32 v1, 1.0, v1
	v_rcp_f32_e32 v21, v1
	s_waitcnt vmcnt(4)
	v_lshlrev_b32_e32 v49, 16, v50
	v_pk_fma_f32 v[20:21], v[20:21], 2.0, 1.0 op_sel_hi:[1,0,0] neg_lo:[1,0,0] neg_hi:[1,0,0]
	s_waitcnt vmcnt(1)
	v_lshlrev_b32_e32 v55, 16, v54
	v_pk_add_f32 v[20:21], v[20:21], 1.0 op_sel_hi:[1,0]
	v_and_b32_e32 v54, 0xffff0000, v54
	v_pk_mul_f32 v[20:21], v[28:29], v[20:21]
	v_lshlrev_b32_e32 v28, 16, v33
	v_pk_mul_f32 v[20:21], v[18:19], v[20:21]
	v_and_b32_e32 v29, 0xffff0000, v33
	v_cvt_pk_bf16_f32 v1, v20, v21
	global_store_dword v[2:3], v1, off
	v_lshlrev_b32_e32 v1, 16, v32
	v_mul_f32_e32 v1, 0x3fb8aa3b, v1
	v_exp_f32_e32 v20, v1
	v_and_b32_e32 v1, 0xffff0000, v32
	v_mul_f32_e32 v1, 0x3fb8aa3b, v1
	v_exp_f32_e32 v21, v1
	v_mul_f32_e32 v1, 0x3d372713, v30
	v_mul_f32_e32 v1, v1, v30
	v_lshlrev_b32_e32 v32, 16, v40
	v_pk_fma_f32 v[18:19], v[18:19], v[20:21], v[28:29]
	v_mov_b32_e32 v20, v30
	v_fmac_f32_e32 v20, v1, v20
	v_mul_f32_e32 v1, 0x3f4c422a, v20
	v_add_f32_e32 v1, v1, v1
	v_mul_f32_e32 v1, 0x3fb8aa3b, v1
	v_exp_f32_e32 v1, v1
	v_mov_b32_e32 v21, v31
	v_pk_mul_f32 v[28:29], v[30:31], 0.5 op_sel_hi:[1,0]
	v_and_b32_e32 v33, 0xffff0000, v40
	v_add_f32_e32 v1, 1.0, v1
	v_rcp_f32_e32 v20, v1
	v_mul_f32_e32 v1, 0x3d372713, v31
	v_mul_f32_e32 v1, v1, v31
	v_fmac_f32_e32 v21, v1, v21
	v_mul_f32_e32 v1, 0x3f4c422a, v21
	v_add_f32_e32 v1, v1, v1
	v_mul_f32_e32 v1, 0x3fb8aa3b, v1
	v_exp_f32_e32 v1, v1
	v_lshlrev_b32_e32 v31, 16, v39
	v_and_b32_e32 v30, 0xffff0000, v39
	v_and_b32_e32 v39, 0xffff0000, v43
	v_add_f32_e32 v1, 1.0, v1
	v_rcp_f32_e32 v21, v1
	v_lshl_add_u64 v[2:3], v[2:3], 0, s[6:7]
	v_pk_fma_f32 v[20:21], v[20:21], 2.0, 1.0 op_sel_hi:[1,0,0] neg_lo:[1,0,0] neg_hi:[1,0,0]
	s_nop 0
	v_pk_add_f32 v[20:21], v[20:21], 1.0 op_sel_hi:[1,0]
	s_nop 0
	v_pk_mul_f32 v[20:21], v[28:29], v[20:21]
	s_nop 0
	v_pk_mul_f32 v[20:21], v[18:19], v[20:21]
	s_nop 0
	v_cvt_pk_bf16_f32 v1, v20, v21
	global_store_dword v[16:17], v1, off offset:1024
	v_lshlrev_b32_e32 v1, 16, v35
	v_mul_f32_e32 v1, 0x3fb8aa3b, v1
	v_exp_f32_e32 v16, v1
	v_and_b32_e32 v1, 0xffff0000, v35
	v_mul_f32_e32 v1, 0x3fb8aa3b, v1
	v_exp_f32_e32 v17, v1
	v_lshlrev_b32_e32 v1, 16, v38
	v_mul_f32_e32 v1, 0x3fb8aa3b, v1
	v_exp_f32_e32 v29, v1
	v_and_b32_e32 v1, 0xffff0000, v38
	v_mul_f32_e32 v1, 0x3fb8aa3b, v1
	v_exp_f32_e32 v28, v1
	v_lshlrev_b32_e32 v1, 16, v41
	v_mul_f32_e32 v1, 0x3fb8aa3b, v1
	v_exp_f32_e32 v35, v1
	v_and_b32_e32 v1, 0xffff0000, v41
	v_mul_f32_e32 v1, 0x3fb8aa3b, v1
	v_exp_f32_e32 v34, v1
	v_lshlrev_b32_e32 v1, 16, v44
	v_mul_f32_e32 v1, 0x3fb8aa3b, v1
	v_exp_f32_e32 v41, v1
	v_and_b32_e32 v1, 0xffff0000, v44
	v_mul_f32_e32 v1, 0x3fb8aa3b, v1
	v_exp_f32_e32 v40, v1
	v_lshlrev_b32_e32 v1, 16, v48
	v_mul_f32_e32 v1, 0x3fb8aa3b, v1
	v_exp_f32_e32 v47, v1
	v_and_b32_e32 v1, 0xffff0000, v48
	v_mul_f32_e32 v1, 0x3fb8aa3b, v1
	v_lshlrev_b32_e32 v21, 16, v36
	v_pk_mul_f32 v[16:17], v[18:19], v[16:17]
	v_and_b32_e32 v20, 0xffff0000, v36
	v_lshlrev_b32_e32 v18, 16, v37
	v_and_b32_e32 v19, 0xffff0000, v37
	v_lshlrev_b32_e32 v37, 16, v42
	v_and_b32_e32 v36, 0xffff0000, v42
	v_lshlrev_b32_e32 v38, 16, v43
	v_lshlrev_b32_e32 v43, 16, v45
	v_and_b32_e32 v42, 0xffff0000, v45
	v_lshlrev_b32_e32 v44, 16, v46
	v_and_b32_e32 v45, 0xffff0000, v46
	v_exp_f32_e32 v46, v1
	v_lshlrev_b32_e32 v1, 16, v52
	v_mul_f32_e32 v1, 0x3fb8aa3b, v1
	v_exp_f32_e32 v53, v1
	v_and_b32_e32 v1, 0xffff0000, v52
	v_mul_f32_e32 v1, 0x3fb8aa3b, v1
	v_exp_f32_e32 v52, v1
	v_mul_f32_e32 v1, 0x3d372713, v18
	v_pk_add_f32 v[16:17], v[16:17], v[20:21] op_sel:[1,0] op_sel_hi:[0,1]
	v_mul_f32_e32 v1, v1, v18
	v_mov_b32_e32 v20, v18
	v_fmac_f32_e32 v20, v1, v20
	v_mul_f32_e32 v1, 0x3f4c422a, v20
	v_add_f32_e32 v1, v1, v1
	v_mul_f32_e32 v1, 0x3fb8aa3b, v1
	v_exp_f32_e32 v1, v1
	v_mov_b32_e32 v21, v19
	v_and_b32_e32 v48, 0xffff0000, v50
	v_lshlrev_b32_e32 v50, 16, v51
	v_add_f32_e32 v1, 1.0, v1
	v_rcp_f32_e32 v20, v1
	v_mul_f32_e32 v1, 0x3d372713, v19
	v_mul_f32_e32 v1, v1, v19
	v_fmac_f32_e32 v21, v1, v21
	v_mul_f32_e32 v1, 0x3f4c422a, v21
	v_add_f32_e32 v1, v1, v1
	v_mul_f32_e32 v1, 0x3fb8aa3b, v1
	v_exp_f32_e32 v1, v1
	v_pk_mul_f32 v[18:19], v[18:19], 0.5 op_sel_hi:[1,0]
	v_and_b32_e32 v51, 0xffff0000, v51
	v_add_f32_e32 v1, 1.0, v1
	v_rcp_f32_e32 v21, v1
	s_nop 0
	v_pk_fma_f32 v[20:21], v[20:21], 2.0, 1.0 op_sel_hi:[1,0,0] neg_lo:[1,0,0] neg_hi:[1,0,0]
	s_nop 0
	v_pk_add_f32 v[20:21], v[20:21], 1.0 op_sel_hi:[1,0]
	s_nop 0
	v_pk_mul_f32 v[18:19], v[18:19], v[20:21]
	s_nop 0
	v_pk_mul_f32 v[18:19], v[16:17], v[18:19] op_sel:[1,0] op_sel_hi:[0,1]
	v_cvt_pk_bf16_f32 v1, v18, v19
	global_store_dword v[14:15], v1, off offset:2048
	v_mul_f32_e32 v1, 0x3d372713, v32
	v_pk_fma_f32 v[14:15], v[16:17], v[28:29], v[30:31]
	v_mul_f32_e32 v1, v1, v32
	v_mov_b32_e32 v16, v32
	v_fmac_f32_e32 v16, v1, v16
	v_mul_f32_e32 v1, 0x3f4c422a, v16
	v_add_f32_e32 v1, v1, v1
	v_mul_f32_e32 v1, 0x3fb8aa3b, v1
	v_exp_f32_e32 v1, v1
	v_mov_b32_e32 v17, v33
	v_pk_mul_f32 v[18:19], v[32:33], 0.5 op_sel_hi:[1,0]
	v_add_f32_e32 v1, 1.0, v1
	v_rcp_f32_e32 v16, v1
	v_mul_f32_e32 v1, 0x3d372713, v33
	v_mul_f32_e32 v1, v1, v33
	v_fmac_f32_e32 v17, v1, v17
	v_mul_f32_e32 v1, 0x3f4c422a, v17
	v_add_f32_e32 v1, v1, v1
	v_mul_f32_e32 v1, 0x3fb8aa3b, v1
	v_exp_f32_e32 v1, v1
	s_nop 0
	v_add_f32_e32 v1, 1.0, v1
	v_rcp_f32_e32 v17, v1
	s_nop 0
	v_pk_fma_f32 v[16:17], v[16:17], 2.0, 1.0 op_sel_hi:[1,0,0] neg_lo:[1,0,0] neg_hi:[1,0,0]
	s_nop 0
	v_pk_add_f32 v[16:17], v[16:17], 1.0 op_sel_hi:[1,0]
	s_nop 0
	v_pk_mul_f32 v[16:17], v[18:19], v[16:17]
	s_nop 0
	v_pk_mul_f32 v[16:17], v[14:15], v[16:17] op_sel:[1,0] op_sel_hi:[0,1]
	v_cvt_pk_bf16_f32 v1, v16, v17
	global_store_dword v[6:7], v1, off offset:3072
	v_mul_f32_e32 v1, 0x3d372713, v38
	v_pk_fma_f32 v[6:7], v[14:15], v[34:35], v[36:37]
	v_mul_f32_e32 v1, v1, v38
	v_mov_b32_e32 v14, v38
	v_fmac_f32_e32 v14, v1, v14
	v_mul_f32_e32 v1, 0x3f4c422a, v14
	v_add_f32_e32 v1, v1, v1
	v_mul_f32_e32 v1, 0x3fb8aa3b, v1
	v_exp_f32_e32 v1, v1
	v_mov_b32_e32 v15, v39
	v_pk_mul_f32 v[16:17], v[38:39], 0.5 op_sel_hi:[1,0]
	v_add_f32_e32 v1, 1.0, v1
	v_rcp_f32_e32 v14, v1
	v_mul_f32_e32 v1, 0x3d372713, v39
	v_mul_f32_e32 v1, v1, v39
	v_fmac_f32_e32 v15, v1, v15
	v_mul_f32_e32 v1, 0x3f4c422a, v15
	v_add_f32_e32 v1, v1, v1
	v_mul_f32_e32 v1, 0x3fb8aa3b, v1
	v_exp_f32_e32 v1, v1
	s_nop 0
	v_add_f32_e32 v1, 1.0, v1
	v_rcp_f32_e32 v15, v1
	s_nop 0
	v_pk_fma_f32 v[14:15], v[14:15], 2.0, 1.0 op_sel_hi:[1,0,0] neg_lo:[1,0,0] neg_hi:[1,0,0]
	s_nop 0
	v_pk_add_f32 v[14:15], v[14:15], 1.0 op_sel_hi:[1,0]
	s_nop 0
	v_pk_mul_f32 v[14:15], v[16:17], v[14:15]
	s_nop 0
	v_pk_mul_f32 v[14:15], v[6:7], v[14:15] op_sel:[1,0] op_sel_hi:[0,1]
	v_cvt_pk_bf16_f32 v1, v14, v15
	global_store_dword v[12:13], v1, off
	v_mul_f32_e32 v1, 0x3d372713, v44
	v_mul_f32_e32 v1, v1, v44
	v_mov_b32_e32 v12, v44
	v_fmac_f32_e32 v12, v1, v12
	v_mul_f32_e32 v1, 0x3f4c422a, v12
	v_add_f32_e32 v1, v1, v1
	v_mul_f32_e32 v1, 0x3fb8aa3b, v1
	v_exp_f32_e32 v1, v1
	v_mov_b32_e32 v13, v45
	v_pk_mul_f32 v[14:15], v[44:45], 0.5 op_sel_hi:[1,0]
	v_pk_fma_f32 v[6:7], v[6:7], v[40:41], v[42:43]
	v_add_f32_e32 v1, 1.0, v1
	v_rcp_f32_e32 v12, v1
	v_mul_f32_e32 v1, 0x3d372713, v45
	v_mul_f32_e32 v1, v1, v45
	v_fmac_f32_e32 v13, v1, v13
	v_mul_f32_e32 v1, 0x3f4c422a, v13
	v_add_f32_e32 v1, v1, v1
	v_mul_f32_e32 v1, 0x3fb8aa3b, v1
	v_exp_f32_e32 v1, v1
	s_nop 0
	v_add_f32_e32 v1, 1.0, v1
	v_rcp_f32_e32 v13, v1
	s_nop 0
	v_pk_fma_f32 v[12:13], v[12:13], 2.0, 1.0 op_sel_hi:[1,0,0] neg_lo:[1,0,0] neg_hi:[1,0,0]
	s_nop 0
	v_pk_add_f32 v[12:13], v[12:13], 1.0 op_sel_hi:[1,0]
	s_nop 0
	v_pk_mul_f32 v[12:13], v[14:15], v[12:13]
	s_nop 0
	v_pk_mul_f32 v[12:13], v[6:7], v[12:13] op_sel:[1,0] op_sel_hi:[0,1]
	v_cvt_pk_bf16_f32 v1, v12, v13
	global_store_dword v[10:11], v1, off offset:1024
	v_mul_f32_e32 v1, 0x3d372713, v50
	v_mul_f32_e32 v1, v1, v50
	v_mov_b32_e32 v10, v50
	v_fmac_f32_e32 v10, v1, v10
	v_mul_f32_e32 v1, 0x3f4c422a, v10
	v_add_f32_e32 v1, v1, v1
	v_mul_f32_e32 v1, 0x3fb8aa3b, v1
	v_exp_f32_e32 v1, v1
	v_mov_b32_e32 v11, v51
	v_pk_mul_f32 v[12:13], v[50:51], 0.5 op_sel_hi:[1,0]
	v_pk_fma_f32 v[6:7], v[6:7], v[46:47], v[48:49]
	v_add_f32_e32 v1, 1.0, v1
	v_rcp_f32_e32 v10, v1
	v_mul_f32_e32 v1, 0x3d372713, v51
	v_mul_f32_e32 v1, v1, v51
	v_fmac_f32_e32 v11, v1, v11
	v_mul_f32_e32 v1, 0x3f4c422a, v11
	v_add_f32_e32 v1, v1, v1
	v_mul_f32_e32 v1, 0x3fb8aa3b, v1
	v_exp_f32_e32 v1, v1
	v_pk_fma_f32 v[28:29], v[6:7], v[52:53], v[54:55]
	v_add_f32_e32 v1, 1.0, v1
	v_rcp_f32_e32 v11, v1
	s_nop 0
	v_pk_fma_f32 v[10:11], v[10:11], 2.0, 1.0 op_sel_hi:[1,0,0] neg_lo:[1,0,0] neg_hi:[1,0,0]
	s_nop 0
	v_pk_add_f32 v[10:11], v[10:11], 1.0 op_sel_hi:[1,0]
	s_nop 0
	v_pk_mul_f32 v[10:11], v[12:13], v[10:11]
	s_nop 0
	v_pk_mul_f32 v[10:11], v[6:7], v[10:11] op_sel:[1,0] op_sel_hi:[0,1]
	v_cvt_pk_bf16_f32 v1, v10, v11
	s_waitcnt vmcnt(6)
	v_lshlrev_b32_e32 v6, 16, v56
	global_store_dword v[8:9], v1, off offset:2048
	v_mul_f32_e32 v1, 0x3d372713, v6
	v_mul_f32_e32 v1, v1, v6
	v_mov_b32_e32 v8, v6
	v_fmac_f32_e32 v8, v1, v8
	v_mul_f32_e32 v1, 0x3f4c422a, v8
	v_add_f32_e32 v1, v1, v1
	v_mul_f32_e32 v1, 0x3fb8aa3b, v1
	v_exp_f32_e32 v1, v1
	v_and_b32_e32 v7, 0xffff0000, v56
	v_mov_b32_e32 v9, v7
	v_add_f32_e32 v1, 1.0, v1
	v_rcp_f32_e32 v8, v1
	v_mul_f32_e32 v1, 0x3d372713, v7
	v_mul_f32_e32 v1, v1, v7
	v_fmac_f32_e32 v9, v1, v9
	v_mul_f32_e32 v1, 0x3f4c422a, v9
	v_add_f32_e32 v1, v1, v1
	v_mul_f32_e32 v1, 0x3fb8aa3b, v1
	v_exp_f32_e32 v1, v1
	v_pk_mul_f32 v[6:7], v[6:7], 0.5 op_sel_hi:[1,0]
	v_add_f32_e32 v1, 1.0, v1
	v_rcp_f32_e32 v9, v1
	s_nop 0
	v_pk_fma_f32 v[8:9], v[8:9], 2.0, 1.0 op_sel_hi:[1,0,0] neg_lo:[1,0,0] neg_hi:[1,0,0]
	s_nop 0
	v_pk_add_f32 v[8:9], v[8:9], 1.0 op_sel_hi:[1,0]
	s_nop 0
	v_pk_mul_f32 v[6:7], v[6:7], v[8:9]
	s_nop 0
	v_pk_mul_f32 v[6:7], v[28:29], v[6:7] op_sel:[1,0] op_sel_hi:[0,1]
	v_cvt_pk_bf16_f32 v1, v6, v7
	global_store_dword v[4:5], v1, off offset:3072
	s_cbranch_scc0 .LBB0_1336
	s_mov_b32 s2, s70
	s_add_i32 s4, s2, s4
	s_cmpk_gt_i32 s4, 0x1ff
	s_cbranch_scc0 .LBB0_1328
